# HGRN2 scan: 16 short stores per tick widened to 8 dword stores via DPP lane pairing + v_perm
# baseline (speedup 1.0000x reference)
; DI int crow(int r, int hi) { return (r & 3) + 8 * (r >> 2) + 4 * hi; }
; #define HG_LOAD_V(g) do { const int t0_ = HG_T0(g); const bf16* vb_ = ((g) >= 8) ? v1 : v0; \
;         _Pragma("unroll") for (int s = 0; s < 4; ++s) vn[s] = *(const s16x4*)(vb_ + (size_t)(t0_ >> 5) * 65536 + 8 * s); } while (0)
; DI void hgrn_item(int item, const float* lbl, const bf16* U1, const bf16* UC1, const bf16* VT, const bf16* VTC, bf16* OF, bf16* OB, LAS unsigned char* lds) {
;     ...
;                 if (t < NC) HG_LOAD_V(t);
;                 if (have_ob) {
;                     bf16* op = OD + (size_t)(b * SEQ + ob_t0) * 1024 + h * 128 + 32 * wave + l32;
; #pragma unroll
;                     for (int i = 0; i < 16; ++i) op[(size_t)crow(i, hi) * 1024] = (bf16)ob[i];
;                     have_ob = false;
;                 }
.LBB0_420:
	v_lshl_add_u64 v[66:67], s[78:79], 0, v[192:193]
	v_mov_b32_e32 v197, v193
	s_lshr_b32 s0, s83, 5
	v_lshl_add_u64 v[66:67], v[66:67], 0, v[196:197]
	s_lshl_b64 s[78:79], s[0:1], 17
	v_lshl_add_u64 v[66:67], v[66:67], 0, s[78:79]
	global_load_dwordx2 v[102:103], v[66:67], off
	global_load_dwordx2 v[104:105], v[66:67], off offset:16
	global_load_dwordx2 v[98:99], v[66:67], off offset:32
	global_load_dwordx2 v[100:101], v[66:67], off offset:48
	s_andn2_b64 vcc, exec, s[58:59]
	s_cbranch_vccnz .LBB0_422
	s_add_i32 s58, s75, s8
	s_ashr_i32 s59, s58, 31
	s_lshl_b64 s[58:59], s[58:59], 11
	v_lshl_add_u64 v[66:67], v[200:201], 0, s[58:59]
	v_mbcnt_lo_u32_b32 v84, -1, 0
	v_mbcnt_hi_u32_b32 v84, -1, v84
	v_and_b32_e32 v84, 1, v84
	v_mul_u32_u24_e32 v84, 0x7fe, v84
	v_mov_b32_e32 v85, 0
	v_lshl_add_u64 v[66:67], v[66:67], 0, v[84:85]
	v_add_co_u32_e32 v68, vcc, 0x1000, v66
	global_store_dword v[66:67], v246, off
	v_addc_co_u32_e32 v69, vcc, 0, v67, vcc
	global_store_dword v[68:69], v245, off
	v_add_co_u32_e32 v68, vcc, 0x4000, v66
	s_nop 1
	v_addc_co_u32_e32 v69, vcc, 0, v67, vcc
	global_store_dword v[68:69], v244, off
	v_add_co_u32_e32 v68, vcc, 0x5000, v66
	s_nop 1
	v_addc_co_u32_e32 v69, vcc, 0, v67, vcc
	global_store_dword v[68:69], v243, off
	v_add_co_u32_e32 v68, vcc, s17, v66
	s_nop 1
	v_addc_co_u32_e32 v69, vcc, 0, v67, vcc
	global_store_dword v[68:69], v242, off
	v_add_co_u32_e32 v68, vcc, 0x9000, v66
	s_nop 1
	v_addc_co_u32_e32 v69, vcc, 0, v67, vcc
	global_store_dword v[68:69], v241, off
	v_add_co_u32_e32 v68, vcc, 0xc000, v66
	s_nop 1
	v_addc_co_u32_e32 v69, vcc, 0, v67, vcc
	v_add_co_u32_e32 v66, vcc, 0xd000, v66
	global_store_dword v[68:69], v240, off
	v_addc_co_u32_e32 v67, vcc, 0, v67, vcc
	global_store_dword v[66:67], v239, off

; DI unsigned short f2bf(float x) { return (unsigned short)(pk2(x, 0.f) & 0xffffu); }
; DI int crow(int r, int hi) { return (r & 3) + 8 * (r >> 2) + 4 * hi; }
; #define MFMA32(a, b, c) __builtin_amdgcn_mfma_f32_32x32x16_bf16((a), (b), (c), 0, 0, 0)
; DI void hgrn_item(int item, const float* lbl, const bf16* U1, const bf16* UC1, const bf16* VT, const bf16* VTC, bf16* OF, bf16* OB, LAS unsigned char* lds) {
;     ...
;                 if (seg) {
; #pragma unroll
;                     for (int i = 0; i < 16; ++i) { const int si = crow(i, hi); const bool keep = dir ? (si >= l32) : (si <= l32); pT[i] = keep ? pT[i] : 0.f; }
;                     const bf16x8 pf0 = pack8(pT, 0), pf1 = pack8(pT, 1);
;                     o = MFMA32(pf0, vf0, o); o = MFMA32(pf1, vf1, o);
; #pragma unroll
;                     for (int i = 0; i < 16; ++i) ob[i] = f2bf(o[i]);
;                     ob_t0 = t0; have_ob = true;
;                 }
.LBB0_457:
	s_waitcnt lgkmcnt(0)
	v_mfma_f32_32x32x16_bf16 v[2:17], v[178:181], v[106:109], v[2:17]
	ds_read_b128 v[126:129], v248 offset:36608
	ds_read_b128 v[122:125], v248 offset:36640
	ds_read_b128 v[118:121], v248 offset:36672
	ds_read_b128 v[114:117], v248 offset:36704
	s_and_b64 vcc, exec, s[70:71]
	s_cbranch_vccz .LBB0_459
	s_nop 1
	v_cndmask_b32_e64 v82, 0, v82, s[24:25]
	v_cndmask_b32_e64 v83, 0, v83, s[26:27]
	v_cndmask_b32_e64 v84, 0, v84, s[28:29]
	v_cndmask_b32_e64 v85, 0, v85, s[30:31]
	v_cndmask_b32_e64 v86, 0, v86, s[34:35]
	v_cndmask_b32_e64 v87, 0, v87, s[36:37]
	v_cndmask_b32_e64 v88, 0, v88, s[38:39]
	v_cndmask_b32_e64 v89, 0, v89, s[40:41]
	v_cvt_pk_bf16_f32 v82, v82, v83
	v_cvt_pk_bf16_f32 v83, v84, v85
	v_cvt_pk_bf16_f32 v84, v86, v87
	v_cvt_pk_bf16_f32 v85, v88, v89
	v_cndmask_b32_e64 v90, 0, v90, s[42:43]
	v_cndmask_b32_e64 v91, 0, v91, s[44:45]
	v_mfma_f32_32x32x16_bf16 v[66:81], v[82:85], v[110:113], v[66:81]
	v_cndmask_b32_e64 v92, 0, v92, s[46:47]
	v_cndmask_b32_e64 v93, 0, v93, s[48:49]
	v_cndmask_b32_e64 v94, 0, v94, s[52:53]
	v_cndmask_b32_e64 v95, 0, v95, s[50:51]
	v_cndmask_b32_e64 v96, 0, v96, s[54:55]
	v_cndmask_b32_e64 v97, 0, v97, s[56:57]
	v_cvt_pk_bf16_f32 v86, v90, v91
	v_cvt_pk_bf16_f32 v87, v92, v93
	v_cvt_pk_bf16_f32 v88, v94, v95
	v_cvt_pk_bf16_f32 v89, v96, v97
	s_mov_b32 s75, s82
	s_nop 0
	v_mfma_f32_32x32x16_bf16 v[66:81], v[86:89], v[106:109], v[66:81]
	s_nop 11
	v_cvt_pk_bf16_f32 v238, v66, v67
	v_cvt_pk_bf16_f32 v237, v68, v69
	v_cvt_pk_bf16_f32 v236, v70, v71
	v_cvt_pk_bf16_f32 v235, v72, v73
	v_cvt_pk_bf16_f32 v234, v74, v75
	v_cvt_pk_bf16_f32 v233, v76, v77
	v_cvt_pk_bf16_f32 v232, v78, v79
	v_cvt_pk_bf16_f32 v199, v80, v81
	v_mbcnt_lo_u32_b32 v83, -1, 0
	v_mbcnt_hi_u32_b32 v83, -1, v83
	v_and_b32_e32 v83, 1, v83
	v_cmp_eq_u32_e32 vcc, 1, v83
	v_mov_b32_e32 v84, 0x5040100
	v_mov_b32_e32 v85, 0x3020706
	s_nop 0
	v_cndmask_b32_e32 v83, v84, v85, vcc
	v_mov_b32_dpp v82, v238 quad_perm:[1,0,3,2] row_mask:0xf bank_mask:0xf
	v_perm_b32 v246, v82, v238, v83
	v_mov_b32_dpp v82, v237 quad_perm:[1,0,3,2] row_mask:0xf bank_mask:0xf
	v_perm_b32 v245, v82, v237, v83
	v_mov_b32_dpp v82, v236 quad_perm:[1,0,3,2] row_mask:0xf bank_mask:0xf
	v_perm_b32 v244, v82, v236, v83
	v_mov_b32_dpp v82, v235 quad_perm:[1,0,3,2] row_mask:0xf bank_mask:0xf
	v_perm_b32 v243, v82, v235, v83
	v_mov_b32_dpp v82, v234 quad_perm:[1,0,3,2] row_mask:0xf bank_mask:0xf
	v_perm_b32 v242, v82, v234, v83
	v_mov_b32_dpp v82, v233 quad_perm:[1,0,3,2] row_mask:0xf bank_mask:0xf
	v_perm_b32 v241, v82, v233, v83
	v_mov_b32_dpp v82, v232 quad_perm:[1,0,3,2] row_mask:0xf bank_mask:0xf
	v_perm_b32 v240, v82, v232, v83
	v_mov_b32_dpp v82, v199 quad_perm:[1,0,3,2] row_mask:0xf bank_mask:0xf
	v_perm_b32 v239, v82, v199, v83

; DI int crow(int r, int hi) { return (r & 3) + 8 * (r >> 2) + 4 * hi; }
; DI void hgrn_item(int item, const float* lbl, const bf16* U1, const bf16* UC1, const bf16* VT, const bf16* VTC, bf16* OF, bf16* OB, LAS unsigned char* lds) {
;     ...
;         if (have_ob) { bf16* op = OD + (size_t)(b * SEQ + ob_t0) * 1024 + h * 128 + 32 * wave + l32;
; #pragma unroll
;             for (int i = 0; i < 16; ++i) op[(size_t)crow(i, hi) * 1024] = (bf16)ob[i]; }
.LBB0_468:
	s_and_b64 vcc, exec, s[58:59]
	s_waitcnt vmcnt(0)
	s_cbranch_vccnz .LBB0_470
	s_add_i32 s58, s75, s8
	s_ashr_i32 s59, s58, 31
	s_lshl_b64 s[58:59], s[58:59], 11
	v_lshl_add_u64 v[16:17], v[200:201], 0, s[58:59]
	v_mbcnt_lo_u32_b32 v84, -1, 0
	v_mbcnt_hi_u32_b32 v84, -1, v84
	v_and_b32_e32 v84, 1, v84
	v_mul_u32_u24_e32 v84, 0x7fe, v84
	v_mov_b32_e32 v85, 0
	v_lshl_add_u64 v[16:17], v[16:17], 0, v[84:85]
	v_add_co_u32_e32 v32, vcc, 0x1000, v16
	global_store_dword v[16:17], v246, off
	v_addc_co_u32_e32 v33, vcc, 0, v17, vcc
	global_store_dword v[32:33], v245, off
	v_add_co_u32_e32 v32, vcc, 0x4000, v16
	s_nop 1
	v_addc_co_u32_e32 v33, vcc, 0, v17, vcc
	global_store_dword v[32:33], v244, off
	v_add_co_u32_e32 v32, vcc, 0x5000, v16
	s_nop 1
	v_addc_co_u32_e32 v33, vcc, 0, v17, vcc
	global_store_dword v[32:33], v243, off
	v_add_co_u32_e32 v32, vcc, s17, v16
	s_nop 1
	v_addc_co_u32_e32 v33, vcc, 0, v17, vcc
	global_store_dword v[32:33], v242, off
	v_add_co_u32_e32 v32, vcc, 0x9000, v16
	s_nop 1
	v_addc_co_u32_e32 v33, vcc, 0, v17, vcc
	global_store_dword v[32:33], v241, off
	v_add_co_u32_e32 v32, vcc, 0xc000, v16
	s_nop 1
	v_addc_co_u32_e32 v33, vcc, 0, v17, vcc
	v_add_co_u32_e32 v16, vcc, 0xd000, v16
	global_store_dword v[32:33], v240, off
	v_addc_co_u32_e32 v17, vcc, 0, v17, vcc
	global_store_dword v[16:17], v239, off
